# SwiGLU GEMM units: row scales loaded at unit start (before the K loop), no wait in the epilogue
# speedup vs baseline: 1.0014x; 1.0014x over previous
;     __host__ __device__ bool next(int i, Unit& u) const {
;         const long L = (long)i * G + c; if (L >= nwg) return false;
;         int wgid = (int)L; { const int q = nwg / NXCD, r = nwg % NXCD, xcd = wgid % NXCD, off = wgid / NXCD; wgid = (xcd < r ? xcd * (q + 1) : r * (q + 1) + (xcd - r) * q) + off; }
;         const int nig = WGM * nN, gid = wgid / nig, fm = gid * WGM, gsz = (nM - fm) < WGM ? (nM - fm) : WGM;
;         u.pm = fm + ((wgid % nig) % gsz); u.pn = (wgid % nig) / gsz; return true;
;     }
;     __device__ __forceinline__ void operator()(const f32x4 (&acc)[2][2][4][2], const Unit& u, int wr, int wc, int fr, int fq) const {
;     ...
;                 const int row = row0 + ai * HALF + m * 16; const float sc = rs[row];
.LBB0_163:
	v_lshl_add_u32 v236, s22, 8, v1
	v_ashrrev_i32_e32 v237, 31, v236
	v_lshl_add_u64 v[236:237], v[236:237], 2, s[8:9]
	global_load_dword v228, v[236:237], off
	global_load_dword v229, v[236:237], off offset:64
	global_load_dword v230, v[236:237], off offset:128
	global_load_dword v231, v[236:237], off offset:192
	global_load_dword v232, v[236:237], off offset:512
	global_load_dword v233, v[236:237], off offset:576
	global_load_dword v234, v[236:237], off offset:640
	global_load_dword v235, v[236:237], off offset:704
	s_add_i32 s45, s45, 1
	s_mul_i32 s2, s45, s50
	s_mul_hi_u32 s3, s45, s51
	s_add_i32 s3, s3, s2
	s_mul_i32 s2, s45, s51
	s_add_u32 s18, s2, s80
	s_addc_u32 s19, s3, s34
	v_cmp_gt_i64_e32 vcc, s[18:19], v[144:145]
	v_cmp_lt_i64_e64 s[2:3], s[18:19], v[142:143]
	s_cbranch_vccnz .LBB0_165
	s_ashr_i32 s14, s18, 31
	s_lshr_b32 s14, s14, 29
	s_add_i32 s14, s18, s14
	s_ashr_i32 s15, s14, 3
	s_and_b32 s14, s14, -8
	s_sub_i32 s14, s18, s14
	s_cmp_lt_i32 s14, 0
	s_cselect_b32 s16, s35, 0x160
	s_mul_i32 s14, s14, s16
	s_add_i32 s14, s14, s15
	s_mul_hi_i32 s15, s14, 0x2e8ba2e9
	s_lshr_b32 s16, s15, 31
	s_ashr_i32 s15, s15, 5
	s_add_i32 s15, s15, s16
	s_lshl_b32 s16, s15, 3
	s_sub_i32 s17, 0x80, s16
	s_min_i32 s17, s17, 8
	s_abs_i32 s18, s17
	v_cvt_f32_u32_e32 v2, s18
	s_sub_i32 s20, 0, s18
	s_mulk_i32 s15, 0xb0
	s_sub_i32 s15, s14, s15
	v_rcp_iflag_f32_e32 v2, v2
	s_abs_i32 s14, s15
	s_xor_b32 s19, s15, s17
	s_ashr_i32 s19, s19, 31
	v_mul_f32_e32 v2, 0x4f7ffffe, v2
	v_cvt_u32_f32_e32 v2, v2
	s_nop 0
	v_readfirstlane_b32 s21, v2
	s_mul_i32 s20, s20, s21
	s_mul_hi_u32 s20, s21, s20
	s_add_i32 s21, s21, s20
	s_mul_hi_u32 s20, s14, s21
	s_mul_i32 s21, s20, s18
	s_sub_i32 s14, s14, s21
	s_add_i32 s28, s20, 1
	s_sub_i32 s21, s14, s18
	s_cmp_ge_u32 s14, s18
	s_cselect_b32 s20, s28, s20
	s_cselect_b32 s14, s21, s14
	s_add_i32 s21, s20, 1
	s_cmp_ge_u32 s14, s18
	s_cselect_b32 s14, s21, s20
	s_xor_b32 s14, s14, s19
	s_sub_i32 s14, s14, s19
	s_mul_i32 s17, s14, s17
	s_sub_i32 s15, s15, s17
	s_add_i32 s16, s16, s15

; __device__ __forceinline__ unsigned cvt_pk_bf16(float lo, float hi) { unsigned r; asm volatile("v_cvt_pk_f16_f32 %0, %1, %2" : "=v"(r) : "v"(lo), "v"(hi)); return r; }
;     __device__ __forceinline__ void operator()(const f32x4 (&acc)[2][2][4][2], const Unit& u, int wr, int wc, int fr, int fq) const {
;         const int row0 = u.pm * BM + wr * 64 + fr, col0 = u.pn * HALF + wc * 32 + 8 * fq;
; #pragma unroll
;         for (int ai = 0; ai < 2; ++ai)
; #pragma unroll
;             for (int m = 0; m < 4; ++m) {
;                 const int row = row0 + ai * HALF + m * 16; const float sc = rs[row];
;                 const float sc2 = sc * sc, nsl = -1.4426950408889634f * sc;
;                 bf16_t* rowp = O + (size_t)row * ldc + col0;
;                 float h[8];
; #pragma unroll
;                 for (int n = 0; n < 2; ++n)
; #pragma unroll
;                     for (int e = 0; e < 4; ++e) { const float g = acc[ai][0][m][n][e], up = acc[ai][1][m][n][e];
;                         h[4 * n + e] = (g * up) * (sc2 * __builtin_amdgcn_rcpf(1.0f + __builtin_amdgcn_exp2f(g * nsl))); }
;                 u32x4 w; w.x = cvt_pk_bf16(h[0], h[1]); w.y = cvt_pk_bf16(h[2], h[3]); w.z = cvt_pk_bf16(h[4], h[5]); w.w = cvt_pk_bf16(h[6], h[7]);
;                 *(u32x4*)rowp = w;
.LBB0_169:
	v_lshl_add_u32 v146, s22, 8, v1
	v_lshl_or_b32 v158, s55, 7, v153
	v_lshlrev_b32_e32 v159, 1, v158
	v_mad_u32_u24 v174, v146, s54, v159
	s_lshl_b32 s98, s54, 4
	s_lshl_b32 s99, s54, 7
	v_mov_b32_e32 v192, 1.0
	v_mov_b32_e32 v193, 1.0
	v_add_u32_e32 v175, s99, v174
	s_andn2_b64 vcc, exec, s[2:3]
	s_mov_b64 s[2:3], -1
	v_mul_f32_e32 v188, 0xbfb8aa3b, v228
	v_mul_f32_e32 v190, v228, v228
	v_pk_mul_f32 v[164:165], v[118:119], v[188:189] op_sel_hi:[1,0]
	v_pk_mul_f32 v[166:167], v[120:121], v[188:189] op_sel_hi:[1,0]
	v_pk_mul_f32 v[168:169], v[114:115], v[188:189] op_sel_hi:[1,0]
	v_pk_mul_f32 v[170:171], v[116:117], v[188:189] op_sel_hi:[1,0]
	v_exp_f32_e32 v164, v164
	v_exp_f32_e32 v165, v165
	v_exp_f32_e32 v166, v166
	v_exp_f32_e32 v167, v167
	v_exp_f32_e32 v168, v168
	v_exp_f32_e32 v169, v169
	v_exp_f32_e32 v170, v170
	v_exp_f32_e32 v171, v171
	v_pk_add_f32 v[164:165], v[164:165], v[192:193]
	v_pk_add_f32 v[166:167], v[166:167], v[192:193]
	v_pk_add_f32 v[168:169], v[168:169], v[192:193]
	v_pk_add_f32 v[170:171], v[170:171], v[192:193]
	v_rcp_f32_e32 v164, v164
	v_rcp_f32_e32 v165, v165
	v_rcp_f32_e32 v166, v166
	v_rcp_f32_e32 v167, v167
	v_rcp_f32_e32 v168, v168
	v_rcp_f32_e32 v169, v169
	v_rcp_f32_e32 v170, v170
	v_rcp_f32_e32 v171, v171
	v_pk_mul_f32 v[164:165], v[164:165], v[190:191] op_sel_hi:[1,0]
	v_pk_mul_f32 v[166:167], v[166:167], v[190:191] op_sel_hi:[1,0]
	v_pk_mul_f32 v[168:169], v[168:169], v[190:191] op_sel_hi:[1,0]
	v_pk_mul_f32 v[170:171], v[170:171], v[190:191] op_sel_hi:[1,0]
	v_pk_mul_f32 v[126:127], v[118:119], v[126:127]
	v_pk_mul_f32 v[128:129], v[120:121], v[128:129]
	v_pk_mul_f32 v[122:123], v[114:115], v[122:123]
	v_pk_mul_f32 v[124:125], v[116:117], v[124:125]
	v_pk_mul_f32 v[126:127], v[126:127], v[164:165]
	v_pk_mul_f32 v[128:129], v[128:129], v[166:167]
	v_pk_mul_f32 v[122:123], v[122:123], v[168:169]
	v_pk_mul_f32 v[124:125], v[124:125], v[170:171]
	v_cvt_pk_f16_f32 v176, v126, v127
	v_cvt_pk_f16_f32 v177, v128, v129
	v_cvt_pk_f16_f32 v178, v122, v123
	v_cvt_pk_f16_f32 v179, v124, v125
	global_store_dwordx4 v174, v[176:179], s[6:7]
	v_add_u32_e32 v174, s98, v174
	v_mul_f32_e32 v188, 0xbfb8aa3b, v229
	v_mul_f32_e32 v190, v229, v229
	v_pk_mul_f32 v[164:165], v[102:103], v[188:189] op_sel_hi:[1,0]
	v_pk_mul_f32 v[166:167], v[104:105], v[188:189] op_sel_hi:[1,0]
	v_pk_mul_f32 v[168:169], v[98:99], v[188:189] op_sel_hi:[1,0]
	v_pk_mul_f32 v[170:171], v[100:101], v[188:189] op_sel_hi:[1,0]
	v_exp_f32_e32 v164, v164
	v_exp_f32_e32 v165, v165
	v_exp_f32_e32 v166, v166
	v_exp_f32_e32 v167, v167
	v_exp_f32_e32 v168, v168
	v_exp_f32_e32 v169, v169
	v_exp_f32_e32 v170, v170
	v_exp_f32_e32 v171, v171
	v_pk_add_f32 v[164:165], v[164:165], v[192:193]
	v_pk_add_f32 v[166:167], v[166:167], v[192:193]
	v_pk_add_f32 v[168:169], v[168:169], v[192:193]
	v_pk_add_f32 v[170:171], v[170:171], v[192:193]
	v_rcp_f32_e32 v164, v164
	v_rcp_f32_e32 v165, v165
	v_rcp_f32_e32 v166, v166
	v_rcp_f32_e32 v167, v167
	v_rcp_f32_e32 v168, v168
	v_rcp_f32_e32 v169, v169
	v_rcp_f32_e32 v170, v170
	v_rcp_f32_e32 v171, v171
	v_pk_mul_f32 v[164:165], v[164:165], v[190:191] op_sel_hi:[1,0]
	v_pk_mul_f32 v[166:167], v[166:167], v[190:191] op_sel_hi:[1,0]
	v_pk_mul_f32 v[168:169], v[168:169], v[190:191] op_sel_hi:[1,0]
	v_pk_mul_f32 v[170:171], v[170:171], v[190:191] op_sel_hi:[1,0]
	v_pk_mul_f32 v[110:111], v[102:103], v[110:111]
	v_pk_mul_f32 v[112:113], v[104:105], v[112:113]
	v_pk_mul_f32 v[106:107], v[98:99], v[106:107]
	v_pk_mul_f32 v[108:109], v[100:101], v[108:109]
	v_pk_mul_f32 v[110:111], v[110:111], v[164:165]
	v_pk_mul_f32 v[112:113], v[112:113], v[166:167]
	v_pk_mul_f32 v[106:107], v[106:107], v[168:169]
	v_pk_mul_f32 v[108:109], v[108:109], v[170:171]
	v_cvt_pk_f16_f32 v176, v110, v111
	v_cvt_pk_f16_f32 v177, v112, v113
	v_cvt_pk_f16_f32 v178, v106, v107
	v_cvt_pk_f16_f32 v179, v108, v109
	global_store_dwordx4 v174, v[176:179], s[6:7]
	v_add_u32_e32 v174, s98, v174
	v_mul_f32_e32 v188, 0xbfb8aa3b, v230
	v_mul_f32_e32 v190, v230, v230
	v_pk_mul_f32 v[164:165], v[86:87], v[188:189] op_sel_hi:[1,0]
	v_pk_mul_f32 v[166:167], v[88:89], v[188:189] op_sel_hi:[1,0]
	v_pk_mul_f32 v[168:169], v[82:83], v[188:189] op_sel_hi:[1,0]
	v_pk_mul_f32 v[170:171], v[84:85], v[188:189] op_sel_hi:[1,0]
	v_exp_f32_e32 v164, v164
	v_exp_f32_e32 v165, v165
	v_exp_f32_e32 v166, v166
	v_exp_f32_e32 v167, v167
	v_exp_f32_e32 v168, v168
	v_exp_f32_e32 v169, v169
	v_exp_f32_e32 v170, v170
	v_exp_f32_e32 v171, v171
	v_pk_add_f32 v[164:165], v[164:165], v[192:193]
	v_pk_add_f32 v[166:167], v[166:167], v[192:193]
	v_pk_add_f32 v[168:169], v[168:169], v[192:193]
	v_pk_add_f32 v[170:171], v[170:171], v[192:193]
	v_rcp_f32_e32 v164, v164
	v_rcp_f32_e32 v165, v165
	v_rcp_f32_e32 v166, v166
	v_rcp_f32_e32 v167, v167
	v_rcp_f32_e32 v168, v168
	v_rcp_f32_e32 v169, v169
	v_rcp_f32_e32 v170, v170
	v_rcp_f32_e32 v171, v171
	v_pk_mul_f32 v[164:165], v[164:165], v[190:191] op_sel_hi:[1,0]
	v_pk_mul_f32 v[166:167], v[166:167], v[190:191] op_sel_hi:[1,0]
	v_pk_mul_f32 v[168:169], v[168:169], v[190:191] op_sel_hi:[1,0]
	v_pk_mul_f32 v[170:171], v[170:171], v[190:191] op_sel_hi:[1,0]
	v_pk_mul_f32 v[94:95], v[86:87], v[94:95]
	v_pk_mul_f32 v[96:97], v[88:89], v[96:97]
	v_pk_mul_f32 v[90:91], v[82:83], v[90:91]
	v_pk_mul_f32 v[92:93], v[84:85], v[92:93]
	v_pk_mul_f32 v[94:95], v[94:95], v[164:165]
	v_pk_mul_f32 v[96:97], v[96:97], v[166:167]
	v_pk_mul_f32 v[90:91], v[90:91], v[168:169]
	v_pk_mul_f32 v[92:93], v[92:93], v[170:171]
	v_cvt_pk_f16_f32 v176, v94, v95
	v_cvt_pk_f16_f32 v177, v96, v97
	v_cvt_pk_f16_f32 v178, v90, v91
	v_cvt_pk_f16_f32 v179, v92, v93
; __device__ __forceinline__ unsigned cvt_pk_bf16(float lo, float hi) { unsigned r; asm volatile("v_cvt_pk_f16_f32 %0, %1, %2" : "=v"(r) : "v"(lo), "v"(hi)); return r; }
;     __device__ __forceinline__ void operator()(const f32x4 (&acc)[2][2][4][2], const Unit& u, int wr, int wc, int fr, int fq) const {
;     ...
;             for (int m = 0; m < 4; ++m) {
;                 const int row = row0 + ai * HALF + m * 16; const float sc = rs[row];
;                 const float sc2 = sc * sc, nsl = -1.4426950408889634f * sc;
;                 bf16_t* rowp = O + (size_t)row * ldc + col0;
;                 float h[8];
; #pragma unroll
;                 for (int n = 0; n < 2; ++n)
; #pragma unroll
;                     for (int e = 0; e < 4; ++e) { const float g = acc[ai][0][m][n][e], up = acc[ai][1][m][n][e];
;                         h[4 * n + e] = (g * up) * (sc2 * __builtin_amdgcn_rcpf(1.0f + __builtin_amdgcn_exp2f(g * nsl))); }
;                 u32x4 w; w.x = cvt_pk_bf16(h[0], h[1]); w.y = cvt_pk_bf16(h[2], h[3]); w.z = cvt_pk_bf16(h[4], h[5]); w.w = cvt_pk_bf16(h[6], h[7]);
;                 *(u32x4*)rowp = w;
	global_store_dwordx4 v174, v[176:179], s[6:7]
	v_add_u32_e32 v174, s98, v174
	v_mul_f32_e32 v188, 0xbfb8aa3b, v231
	v_mul_f32_e32 v190, v231, v231
	v_pk_mul_f32 v[164:165], v[70:71], v[188:189] op_sel_hi:[1,0]
	v_pk_mul_f32 v[166:167], v[72:73], v[188:189] op_sel_hi:[1,0]
	v_pk_mul_f32 v[168:169], v[66:67], v[188:189] op_sel_hi:[1,0]
	v_pk_mul_f32 v[170:171], v[68:69], v[188:189] op_sel_hi:[1,0]
	v_exp_f32_e32 v164, v164
	v_exp_f32_e32 v165, v165
	v_exp_f32_e32 v166, v166
	v_exp_f32_e32 v167, v167
	v_exp_f32_e32 v168, v168
	v_exp_f32_e32 v169, v169
	v_exp_f32_e32 v170, v170
	v_exp_f32_e32 v171, v171
	v_pk_add_f32 v[164:165], v[164:165], v[192:193]
	v_pk_add_f32 v[166:167], v[166:167], v[192:193]
	v_pk_add_f32 v[168:169], v[168:169], v[192:193]
	v_pk_add_f32 v[170:171], v[170:171], v[192:193]
	v_rcp_f32_e32 v164, v164
	v_rcp_f32_e32 v165, v165
	v_rcp_f32_e32 v166, v166
	v_rcp_f32_e32 v167, v167
	v_rcp_f32_e32 v168, v168
	v_rcp_f32_e32 v169, v169
	v_rcp_f32_e32 v170, v170
	v_rcp_f32_e32 v171, v171
	v_pk_mul_f32 v[164:165], v[164:165], v[190:191] op_sel_hi:[1,0]
	v_pk_mul_f32 v[166:167], v[166:167], v[190:191] op_sel_hi:[1,0]
	v_pk_mul_f32 v[168:169], v[168:169], v[190:191] op_sel_hi:[1,0]
	v_pk_mul_f32 v[170:171], v[170:171], v[190:191] op_sel_hi:[1,0]
	v_pk_mul_f32 v[78:79], v[70:71], v[78:79]
	v_pk_mul_f32 v[80:81], v[72:73], v[80:81]
	v_pk_mul_f32 v[74:75], v[66:67], v[74:75]
	v_pk_mul_f32 v[76:77], v[68:69], v[76:77]
	v_pk_mul_f32 v[78:79], v[78:79], v[164:165]
	v_pk_mul_f32 v[80:81], v[80:81], v[166:167]
	v_pk_mul_f32 v[74:75], v[74:75], v[168:169]
	v_pk_mul_f32 v[76:77], v[76:77], v[170:171]
	v_cvt_pk_f16_f32 v176, v78, v79
	v_cvt_pk_f16_f32 v177, v80, v81
	v_cvt_pk_f16_f32 v178, v74, v75
	v_cvt_pk_f16_f32 v179, v76, v77
	global_store_dwordx4 v174, v[176:179], s[6:7]
	v_mul_f32_e32 v188, 0xbfb8aa3b, v232
	v_mul_f32_e32 v190, v232, v232
	v_pk_mul_f32 v[164:165], v[54:55], v[188:189] op_sel_hi:[1,0]
	v_pk_mul_f32 v[166:167], v[56:57], v[188:189] op_sel_hi:[1,0]
	v_pk_mul_f32 v[168:169], v[50:51], v[188:189] op_sel_hi:[1,0]
	v_pk_mul_f32 v[170:171], v[52:53], v[188:189] op_sel_hi:[1,0]
	v_exp_f32_e32 v164, v164
	v_exp_f32_e32 v165, v165
	v_exp_f32_e32 v166, v166
	v_exp_f32_e32 v167, v167
	v_exp_f32_e32 v168, v168
	v_exp_f32_e32 v169, v169
	v_exp_f32_e32 v170, v170
	v_exp_f32_e32 v171, v171
	v_pk_add_f32 v[164:165], v[164:165], v[192:193]
	v_pk_add_f32 v[166:167], v[166:167], v[192:193]
	v_pk_add_f32 v[168:169], v[168:169], v[192:193]
	v_pk_add_f32 v[170:171], v[170:171], v[192:193]
	v_rcp_f32_e32 v164, v164
	v_rcp_f32_e32 v165, v165
	v_rcp_f32_e32 v166, v166
	v_rcp_f32_e32 v167, v167
	v_rcp_f32_e32 v168, v168
	v_rcp_f32_e32 v169, v169
	v_rcp_f32_e32 v170, v170
	v_rcp_f32_e32 v171, v171
	v_pk_mul_f32 v[164:165], v[164:165], v[190:191] op_sel_hi:[1,0]
	v_pk_mul_f32 v[166:167], v[166:167], v[190:191] op_sel_hi:[1,0]
	v_pk_mul_f32 v[168:169], v[168:169], v[190:191] op_sel_hi:[1,0]
	v_pk_mul_f32 v[170:171], v[170:171], v[190:191] op_sel_hi:[1,0]
	v_pk_mul_f32 v[62:63], v[54:55], v[62:63]
	v_pk_mul_f32 v[64:65], v[56:57], v[64:65]
	v_pk_mul_f32 v[58:59], v[50:51], v[58:59]
	v_pk_mul_f32 v[60:61], v[52:53], v[60:61]
	v_pk_mul_f32 v[62:63], v[62:63], v[164:165]
	v_pk_mul_f32 v[64:65], v[64:65], v[166:167]
	v_pk_mul_f32 v[58:59], v[58:59], v[168:169]
	v_pk_mul_f32 v[60:61], v[60:61], v[170:171]
	v_cvt_pk_f16_f32 v176, v62, v63
	v_cvt_pk_f16_f32 v177, v64, v65
	v_cvt_pk_f16_f32 v178, v58, v59
	v_cvt_pk_f16_f32 v179, v60, v61
	global_store_dwordx4 v175, v[176:179], s[6:7]
	v_add_u32_e32 v175, s98, v175
	v_mul_f32_e32 v188, 0xbfb8aa3b, v233
	v_mul_f32_e32 v190, v233, v233
	v_pk_mul_f32 v[164:165], v[38:39], v[188:189] op_sel_hi:[1,0]
	v_pk_mul_f32 v[166:167], v[40:41], v[188:189] op_sel_hi:[1,0]
	v_pk_mul_f32 v[168:169], v[34:35], v[188:189] op_sel_hi:[1,0]
	v_pk_mul_f32 v[170:171], v[36:37], v[188:189] op_sel_hi:[1,0]
	v_exp_f32_e32 v164, v164
	v_exp_f32_e32 v165, v165
	v_exp_f32_e32 v166, v166
	v_exp_f32_e32 v167, v167
	v_exp_f32_e32 v168, v168
	v_exp_f32_e32 v169, v169
	v_exp_f32_e32 v170, v170
	v_exp_f32_e32 v171, v171
	v_pk_add_f32 v[164:165], v[164:165], v[192:193]
	v_pk_add_f32 v[166:167], v[166:167], v[192:193]
	v_pk_add_f32 v[168:169], v[168:169], v[192:193]
	v_pk_add_f32 v[170:171], v[170:171], v[192:193]
	v_rcp_f32_e32 v164, v164
	v_rcp_f32_e32 v165, v165
	v_rcp_f32_e32 v166, v166
	v_rcp_f32_e32 v167, v167
	v_rcp_f32_e32 v168, v168
	v_rcp_f32_e32 v169, v169
; __device__ __forceinline__ unsigned cvt_pk_bf16(float lo, float hi) { unsigned r; asm volatile("v_cvt_pk_f16_f32 %0, %1, %2" : "=v"(r) : "v"(lo), "v"(hi)); return r; }
; #define PG8_BAR __builtin_amdgcn_s_barrier()
; template <class Epi, class Sched, bool ALIGN_EPI = false, bool SP2 = false>
; __device__ __forceinline__ void gemm_phase(PG8_LAS unsigned char* lds, const Gemm g, const Sched& S, const Epi& E) {
;     ...
;         if (!has_next) break;
; #pragma unroll
;         for (int a = 0; a < 2; ++a)
; #pragma unroll
;             for (int b = 0; b < 2; ++b)
; #pragma unroll
;                 for (int m = 0; m < 4; ++m)
; #pragma unroll
;                     for (int n = 0; n < 2; ++n) acc[a][b][m][n] = (f32x4){0.f, 0.f, 0.f, 0.f};
;         cur = nxt; cA = nA; cB = nB; ++ui;
;         if constexpr (ALIGN_EPI) { if (wr == 1) PG8_BAR; }
;     __device__ __forceinline__ void operator()(const f32x4 (&acc)[2][2][4][2], const Unit& u, int wr, int wc, int fr, int fq) const {
;     ...
;             for (int m = 0; m < 4; ++m) {
;                 const int row = row0 + ai * HALF + m * 16; const float sc = rs[row];
;                 const float sc2 = sc * sc, nsl = -1.4426950408889634f * sc;
;                 bf16_t* rowp = O + (size_t)row * ldc + col0;
;                 float h[8];
; #pragma unroll
;                 for (int n = 0; n < 2; ++n)
; #pragma unroll
;                     for (int e = 0; e < 4; ++e) { const float g = acc[ai][0][m][n][e], up = acc[ai][1][m][n][e];
;                         h[4 * n + e] = (g * up) * (sc2 * __builtin_amdgcn_rcpf(1.0f + __builtin_amdgcn_exp2f(g * nsl))); }
;                 u32x4 w; w.x = cvt_pk_bf16(h[0], h[1]); w.y = cvt_pk_bf16(h[2], h[3]); w.z = cvt_pk_bf16(h[4], h[5]); w.w = cvt_pk_bf16(h[6], h[7]);
;                 *(u32x4*)rowp = w;
	v_rcp_f32_e32 v170, v170
	v_rcp_f32_e32 v171, v171
	v_pk_mul_f32 v[164:165], v[164:165], v[190:191] op_sel_hi:[1,0]
	v_pk_mul_f32 v[166:167], v[166:167], v[190:191] op_sel_hi:[1,0]
	v_pk_mul_f32 v[168:169], v[168:169], v[190:191] op_sel_hi:[1,0]
	v_pk_mul_f32 v[170:171], v[170:171], v[190:191] op_sel_hi:[1,0]
	v_pk_mul_f32 v[46:47], v[38:39], v[46:47]
	v_pk_mul_f32 v[48:49], v[40:41], v[48:49]
	v_pk_mul_f32 v[42:43], v[34:35], v[42:43]
	v_pk_mul_f32 v[44:45], v[36:37], v[44:45]
	v_pk_mul_f32 v[46:47], v[46:47], v[164:165]
	v_pk_mul_f32 v[48:49], v[48:49], v[166:167]
	v_pk_mul_f32 v[42:43], v[42:43], v[168:169]
	v_pk_mul_f32 v[44:45], v[44:45], v[170:171]
	v_cvt_pk_f16_f32 v176, v46, v47
	v_cvt_pk_f16_f32 v177, v48, v49
	v_cvt_pk_f16_f32 v178, v42, v43
	v_cvt_pk_f16_f32 v179, v44, v45
	global_store_dwordx4 v175, v[176:179], s[6:7]
	v_add_u32_e32 v175, s98, v175
	v_mul_f32_e32 v188, 0xbfb8aa3b, v234
	v_mul_f32_e32 v190, v234, v234
	v_pk_mul_f32 v[164:165], v[22:23], v[188:189] op_sel_hi:[1,0]
	v_pk_mul_f32 v[166:167], v[24:25], v[188:189] op_sel_hi:[1,0]
	v_pk_mul_f32 v[168:169], v[18:19], v[188:189] op_sel_hi:[1,0]
	v_pk_mul_f32 v[170:171], v[20:21], v[188:189] op_sel_hi:[1,0]
	v_exp_f32_e32 v164, v164
	v_exp_f32_e32 v165, v165
	v_exp_f32_e32 v166, v166
	v_exp_f32_e32 v167, v167
	v_exp_f32_e32 v168, v168
	v_exp_f32_e32 v169, v169
	v_exp_f32_e32 v170, v170
	v_exp_f32_e32 v171, v171
	v_pk_add_f32 v[164:165], v[164:165], v[192:193]
	v_pk_add_f32 v[166:167], v[166:167], v[192:193]
	v_pk_add_f32 v[168:169], v[168:169], v[192:193]
	v_pk_add_f32 v[170:171], v[170:171], v[192:193]
	v_rcp_f32_e32 v164, v164
	v_rcp_f32_e32 v165, v165
	v_rcp_f32_e32 v166, v166
	v_rcp_f32_e32 v167, v167
	v_rcp_f32_e32 v168, v168
	v_rcp_f32_e32 v169, v169
	v_rcp_f32_e32 v170, v170
	v_rcp_f32_e32 v171, v171
	v_pk_mul_f32 v[164:165], v[164:165], v[190:191] op_sel_hi:[1,0]
	v_pk_mul_f32 v[166:167], v[166:167], v[190:191] op_sel_hi:[1,0]
	v_pk_mul_f32 v[168:169], v[168:169], v[190:191] op_sel_hi:[1,0]
	v_pk_mul_f32 v[170:171], v[170:171], v[190:191] op_sel_hi:[1,0]
	v_pk_mul_f32 v[30:31], v[22:23], v[30:31]
	v_pk_mul_f32 v[32:33], v[24:25], v[32:33]
	v_pk_mul_f32 v[26:27], v[18:19], v[26:27]
	v_pk_mul_f32 v[28:29], v[20:21], v[28:29]
	v_pk_mul_f32 v[30:31], v[30:31], v[164:165]
	v_pk_mul_f32 v[32:33], v[32:33], v[166:167]
	v_pk_mul_f32 v[26:27], v[26:27], v[168:169]
	v_pk_mul_f32 v[28:29], v[28:29], v[170:171]
	v_cvt_pk_f16_f32 v176, v30, v31
	v_cvt_pk_f16_f32 v177, v32, v33
	v_cvt_pk_f16_f32 v178, v26, v27
	v_cvt_pk_f16_f32 v179, v28, v29
	global_store_dwordx4 v175, v[176:179], s[6:7]
	v_add_u32_e32 v175, s98, v175
	v_mul_f32_e32 v188, 0xbfb8aa3b, v235
	v_mul_f32_e32 v190, v235, v235
	v_pk_mul_f32 v[164:165], v[6:7], v[188:189] op_sel_hi:[1,0]
	v_pk_mul_f32 v[166:167], v[8:9], v[188:189] op_sel_hi:[1,0]
	v_pk_mul_f32 v[168:169], v[2:3], v[188:189] op_sel_hi:[1,0]
	v_pk_mul_f32 v[170:171], v[4:5], v[188:189] op_sel_hi:[1,0]
	v_exp_f32_e32 v164, v164
	v_exp_f32_e32 v165, v165
	v_exp_f32_e32 v166, v166
	v_exp_f32_e32 v167, v167
	v_exp_f32_e32 v168, v168
	v_exp_f32_e32 v169, v169
	v_exp_f32_e32 v170, v170
	v_exp_f32_e32 v171, v171
	v_pk_add_f32 v[164:165], v[164:165], v[192:193]
	v_pk_add_f32 v[166:167], v[166:167], v[192:193]
	v_pk_add_f32 v[168:169], v[168:169], v[192:193]
	v_pk_add_f32 v[170:171], v[170:171], v[192:193]
	v_rcp_f32_e32 v164, v164
	v_rcp_f32_e32 v165, v165
	v_rcp_f32_e32 v166, v166
	v_rcp_f32_e32 v167, v167
	v_rcp_f32_e32 v168, v168
	v_rcp_f32_e32 v169, v169
	v_rcp_f32_e32 v170, v170
	v_rcp_f32_e32 v171, v171
	v_pk_mul_f32 v[164:165], v[164:165], v[190:191] op_sel_hi:[1,0]
	v_pk_mul_f32 v[166:167], v[166:167], v[190:191] op_sel_hi:[1,0]
	v_pk_mul_f32 v[168:169], v[168:169], v[190:191] op_sel_hi:[1,0]
	v_pk_mul_f32 v[170:171], v[170:171], v[190:191] op_sel_hi:[1,0]
	v_pk_mul_f32 v[14:15], v[6:7], v[14:15]
	v_pk_mul_f32 v[16:17], v[8:9], v[16:17]
	v_pk_mul_f32 v[10:11], v[2:3], v[10:11]
	v_pk_mul_f32 v[12:13], v[4:5], v[12:13]
	v_pk_mul_f32 v[14:15], v[14:15], v[164:165]
	v_pk_mul_f32 v[16:17], v[16:17], v[166:167]
	v_pk_mul_f32 v[10:11], v[10:11], v[168:169]
	v_pk_mul_f32 v[12:13], v[12:13], v[170:171]
	v_cvt_pk_f16_f32 v176, v14, v15
	v_cvt_pk_f16_f32 v177, v16, v17
	v_cvt_pk_f16_f32 v178, v10, v11
	v_cvt_pk_f16_f32 v179, v12, v13
	global_store_dwordx4 v175, v[176:179], s[6:7]
	s_cbranch_vccnz .LBB0_162
	s_andn2_b64 vcc, exec, s[4:5]
	s_cbranch_vccnz .LBB0_161
	s_barrier
	s_branch .LBB0_161

;     __host__ __device__ bool next(int i, Unit& u) const {
;         const long L = (long)i * G + c; if (L >= nwg) return false;
;         int wgid = (int)L; { const int q = nwg / NXCD, r = nwg % NXCD, xcd = wgid % NXCD, off = wgid / NXCD; wgid = (xcd < r ? xcd * (q + 1) : r * (q + 1) + (xcd - r) * q) + off; }
;         const int nig = WGM * nN, gid = wgid / nig, fm = gid * WGM, gsz = (nM - fm) < WGM ? (nM - fm) : WGM;
;         u.pm = fm + ((wgid % nig) % gsz); u.pn = (wgid % nig) / gsz; return true;
;     }
;     __device__ __forceinline__ void operator()(const f32x4 (&acc)[2][2][4][2], const Unit& u, int wr, int wc, int fr, int fq) const {
;     ...
;                 const int row = row0 + ai * HALF + m * 16; const float sc = rs[row];
.LBB0_1011:
	v_lshl_add_u32 v236, s22, 8, v1
	v_ashrrev_i32_e32 v237, 31, v236
	v_lshl_add_u64 v[236:237], v[236:237], 2, s[8:9]
	global_load_dword v228, v[236:237], off
	global_load_dword v229, v[236:237], off offset:64
	global_load_dword v230, v[236:237], off offset:128
	global_load_dword v231, v[236:237], off offset:192
	global_load_dword v232, v[236:237], off offset:512
	global_load_dword v233, v[236:237], off offset:576
	global_load_dword v234, v[236:237], off offset:640
	global_load_dword v235, v[236:237], off offset:704
	s_add_i32 s39, s39, 1
	s_mul_i32 s2, s39, s42
	s_mul_hi_u32 s3, s39, s43
	s_add_i32 s3, s3, s2
	s_mul_i32 s2, s39, s43
	s_add_u32 s18, s2, s80
	s_addc_u32 s19, s3, s34
	v_cmp_gt_i64_e32 vcc, s[18:19], v[144:145]
	v_cmp_lt_i64_e64 s[2:3], s[18:19], v[142:143]
	s_cbranch_vccnz .LBB0_1013
	s_ashr_i32 s14, s18, 31
	s_lshr_b32 s14, s14, 29
	s_add_i32 s14, s18, s14
	s_ashr_i32 s15, s14, 3
	s_and_b32 s14, s14, -8
	s_sub_i32 s14, s18, s14
	s_cmp_lt_i32 s14, 0
	s_cselect_b32 s16, s35, 0x160
	s_mul_i32 s14, s14, s16
	s_add_i32 s14, s14, s15
	s_mul_hi_i32 s15, s14, 0x2e8ba2e9
	s_lshr_b32 s16, s15, 31
	s_ashr_i32 s15, s15, 5
	s_add_i32 s15, s15, s16
	s_lshl_b32 s16, s15, 3
	s_sub_i32 s17, 0x80, s16
	s_min_i32 s17, s17, 8
	s_abs_i32 s18, s17
	v_cvt_f32_u32_e32 v2, s18
	s_sub_i32 s20, 0, s18
	s_mulk_i32 s15, 0xb0
	s_sub_i32 s15, s14, s15
	v_rcp_iflag_f32_e32 v2, v2
	s_abs_i32 s14, s15
	s_xor_b32 s19, s15, s17
	s_ashr_i32 s19, s19, 31
	v_mul_f32_e32 v2, 0x4f7ffffe, v2
	v_cvt_u32_f32_e32 v2, v2
	s_nop 0
	v_readfirstlane_b32 s21, v2
	s_mul_i32 s20, s20, s21
	s_mul_hi_u32 s20, s21, s20
	s_add_i32 s21, s21, s20
	s_mul_hi_u32 s20, s14, s21
	s_mul_i32 s21, s20, s18
	s_sub_i32 s14, s14, s21
	s_add_i32 s28, s20, 1
	s_sub_i32 s21, s14, s18
	s_cmp_ge_u32 s14, s18
	s_cselect_b32 s20, s28, s20
	s_cselect_b32 s14, s21, s14
	s_add_i32 s21, s20, 1
	s_cmp_ge_u32 s14, s18
	s_cselect_b32 s14, s21, s20
	s_xor_b32 s14, s14, s19
	s_sub_i32 s14, s14, s19
	s_mul_i32 s17, s14, s17
	s_sub_i32 s15, s15, s17
	s_add_i32 s16, s16, s15

; __device__ __forceinline__ unsigned cvt_pk_bf16(float lo, float hi) { unsigned r; asm volatile("v_cvt_pk_f16_f32 %0, %1, %2" : "=v"(r) : "v"(lo), "v"(hi)); return r; }
;     __device__ __forceinline__ void operator()(const f32x4 (&acc)[2][2][4][2], const Unit& u, int wr, int wc, int fr, int fq) const {
;     ...
;                 const int row = row0 + ai * HALF + m * 16; const float sc = rs[row];
;                 const float sc2 = sc * sc, nsl = -1.4426950408889634f * sc;
;                 bf16_t* rowp = O + (size_t)row * ldc + col0;
;                 float h[8];
; #pragma unroll
;                 for (int n = 0; n < 2; ++n)
; #pragma unroll
;                     for (int e = 0; e < 4; ++e) { const float g = acc[ai][0][m][n][e], up = acc[ai][1][m][n][e];
;                         h[4 * n + e] = (g * up) * (sc2 * __builtin_amdgcn_rcpf(1.0f + __builtin_amdgcn_exp2f(g * nsl))); }
;                 u32x4 w; w.x = cvt_pk_bf16(h[0], h[1]); w.y = cvt_pk_bf16(h[2], h[3]); w.z = cvt_pk_bf16(h[4], h[5]); w.w = cvt_pk_bf16(h[6], h[7]);
;                 *(u32x4*)rowp = w;
.LBB0_1017:
	v_lshl_add_u32 v146, s22, 8, v1
	v_lshl_or_b32 v158, s47, 7, v153
	v_lshlrev_b32_e32 v159, 1, v158
	v_mad_u32_u24 v174, v146, s46, v159
	s_lshl_b32 s98, s46, 4
	s_lshl_b32 s99, s46, 7
	v_mov_b32_e32 v192, 1.0
	v_mov_b32_e32 v193, 1.0
	v_add_u32_e32 v175, s99, v174
	s_andn2_b64 vcc, exec, s[2:3]
	s_mov_b64 s[2:3], -1
	v_mul_f32_e32 v188, 0xbfb8aa3b, v228
	v_mul_f32_e32 v190, v228, v228
	v_pk_mul_f32 v[164:165], v[118:119], v[188:189] op_sel_hi:[1,0]
	v_pk_mul_f32 v[166:167], v[120:121], v[188:189] op_sel_hi:[1,0]
	v_pk_mul_f32 v[168:169], v[114:115], v[188:189] op_sel_hi:[1,0]
	v_pk_mul_f32 v[170:171], v[116:117], v[188:189] op_sel_hi:[1,0]
	v_exp_f32_e32 v164, v164
	v_exp_f32_e32 v165, v165
	v_exp_f32_e32 v166, v166
	v_exp_f32_e32 v167, v167
	v_exp_f32_e32 v168, v168
	v_exp_f32_e32 v169, v169
	v_exp_f32_e32 v170, v170
	v_exp_f32_e32 v171, v171
	v_pk_add_f32 v[164:165], v[164:165], v[192:193]
	v_pk_add_f32 v[166:167], v[166:167], v[192:193]
	v_pk_add_f32 v[168:169], v[168:169], v[192:193]
	v_pk_add_f32 v[170:171], v[170:171], v[192:193]
	v_rcp_f32_e32 v164, v164
	v_rcp_f32_e32 v165, v165
	v_rcp_f32_e32 v166, v166
	v_rcp_f32_e32 v167, v167
	v_rcp_f32_e32 v168, v168
	v_rcp_f32_e32 v169, v169
	v_rcp_f32_e32 v170, v170
	v_rcp_f32_e32 v171, v171
	v_pk_mul_f32 v[164:165], v[164:165], v[190:191] op_sel_hi:[1,0]
	v_pk_mul_f32 v[166:167], v[166:167], v[190:191] op_sel_hi:[1,0]
	v_pk_mul_f32 v[168:169], v[168:169], v[190:191] op_sel_hi:[1,0]
	v_pk_mul_f32 v[170:171], v[170:171], v[190:191] op_sel_hi:[1,0]
	v_pk_mul_f32 v[126:127], v[118:119], v[126:127]
	v_pk_mul_f32 v[128:129], v[120:121], v[128:129]
	v_pk_mul_f32 v[122:123], v[114:115], v[122:123]
	v_pk_mul_f32 v[124:125], v[116:117], v[124:125]
	v_pk_mul_f32 v[126:127], v[126:127], v[164:165]
	v_pk_mul_f32 v[128:129], v[128:129], v[166:167]
	v_pk_mul_f32 v[122:123], v[122:123], v[168:169]
	v_pk_mul_f32 v[124:125], v[124:125], v[170:171]
	v_cvt_pk_f16_f32 v176, v126, v127
	v_cvt_pk_f16_f32 v177, v128, v129
	v_cvt_pk_f16_f32 v178, v122, v123
	v_cvt_pk_f16_f32 v179, v124, v125
	global_store_dwordx4 v174, v[176:179], s[6:7]
	v_add_u32_e32 v174, s98, v174
	v_mul_f32_e32 v188, 0xbfb8aa3b, v229
	v_mul_f32_e32 v190, v229, v229
	v_pk_mul_f32 v[164:165], v[102:103], v[188:189] op_sel_hi:[1,0]
	v_pk_mul_f32 v[166:167], v[104:105], v[188:189] op_sel_hi:[1,0]
	v_pk_mul_f32 v[168:169], v[98:99], v[188:189] op_sel_hi:[1,0]
	v_pk_mul_f32 v[170:171], v[100:101], v[188:189] op_sel_hi:[1,0]
	v_exp_f32_e32 v164, v164
	v_exp_f32_e32 v165, v165
	v_exp_f32_e32 v166, v166
	v_exp_f32_e32 v167, v167
	v_exp_f32_e32 v168, v168
	v_exp_f32_e32 v169, v169
	v_exp_f32_e32 v170, v170
	v_exp_f32_e32 v171, v171
	v_pk_add_f32 v[164:165], v[164:165], v[192:193]
	v_pk_add_f32 v[166:167], v[166:167], v[192:193]
	v_pk_add_f32 v[168:169], v[168:169], v[192:193]
	v_pk_add_f32 v[170:171], v[170:171], v[192:193]
	v_rcp_f32_e32 v164, v164
	v_rcp_f32_e32 v165, v165
	v_rcp_f32_e32 v166, v166
	v_rcp_f32_e32 v167, v167
	v_rcp_f32_e32 v168, v168
	v_rcp_f32_e32 v169, v169
	v_rcp_f32_e32 v170, v170
	v_rcp_f32_e32 v171, v171
	v_pk_mul_f32 v[164:165], v[164:165], v[190:191] op_sel_hi:[1,0]
	v_pk_mul_f32 v[166:167], v[166:167], v[190:191] op_sel_hi:[1,0]
	v_pk_mul_f32 v[168:169], v[168:169], v[190:191] op_sel_hi:[1,0]
	v_pk_mul_f32 v[170:171], v[170:171], v[190:191] op_sel_hi:[1,0]
	v_pk_mul_f32 v[110:111], v[102:103], v[110:111]
	v_pk_mul_f32 v[112:113], v[104:105], v[112:113]
	v_pk_mul_f32 v[106:107], v[98:99], v[106:107]
	v_pk_mul_f32 v[108:109], v[100:101], v[108:109]
	v_pk_mul_f32 v[110:111], v[110:111], v[164:165]
	v_pk_mul_f32 v[112:113], v[112:113], v[166:167]
	v_pk_mul_f32 v[106:107], v[106:107], v[168:169]
	v_pk_mul_f32 v[108:109], v[108:109], v[170:171]
	v_cvt_pk_f16_f32 v176, v110, v111
	v_cvt_pk_f16_f32 v177, v112, v113
	v_cvt_pk_f16_f32 v178, v106, v107
	v_cvt_pk_f16_f32 v179, v108, v109
	global_store_dwordx4 v174, v[176:179], s[6:7]
	v_add_u32_e32 v174, s98, v174
	v_mul_f32_e32 v188, 0xbfb8aa3b, v230
	v_mul_f32_e32 v190, v230, v230
	v_pk_mul_f32 v[164:165], v[86:87], v[188:189] op_sel_hi:[1,0]
	v_pk_mul_f32 v[166:167], v[88:89], v[188:189] op_sel_hi:[1,0]
	v_pk_mul_f32 v[168:169], v[82:83], v[188:189] op_sel_hi:[1,0]
	v_pk_mul_f32 v[170:171], v[84:85], v[188:189] op_sel_hi:[1,0]
	v_exp_f32_e32 v164, v164
	v_exp_f32_e32 v165, v165
	v_exp_f32_e32 v166, v166
	v_exp_f32_e32 v167, v167
	v_exp_f32_e32 v168, v168
	v_exp_f32_e32 v169, v169
	v_exp_f32_e32 v170, v170
	v_exp_f32_e32 v171, v171
	v_pk_add_f32 v[164:165], v[164:165], v[192:193]
	v_pk_add_f32 v[166:167], v[166:167], v[192:193]
	v_pk_add_f32 v[168:169], v[168:169], v[192:193]
	v_pk_add_f32 v[170:171], v[170:171], v[192:193]
	v_rcp_f32_e32 v164, v164
	v_rcp_f32_e32 v165, v165
	v_rcp_f32_e32 v166, v166
	v_rcp_f32_e32 v167, v167
	v_rcp_f32_e32 v168, v168
	v_rcp_f32_e32 v169, v169
	v_rcp_f32_e32 v170, v170
	v_rcp_f32_e32 v171, v171
	v_pk_mul_f32 v[164:165], v[164:165], v[190:191] op_sel_hi:[1,0]
	v_pk_mul_f32 v[166:167], v[166:167], v[190:191] op_sel_hi:[1,0]
	v_pk_mul_f32 v[168:169], v[168:169], v[190:191] op_sel_hi:[1,0]
	v_pk_mul_f32 v[170:171], v[170:171], v[190:191] op_sel_hi:[1,0]
	v_pk_mul_f32 v[94:95], v[86:87], v[94:95]
	v_pk_mul_f32 v[96:97], v[88:89], v[96:97]
	v_pk_mul_f32 v[90:91], v[82:83], v[90:91]
	v_pk_mul_f32 v[92:93], v[84:85], v[92:93]
	v_pk_mul_f32 v[94:95], v[94:95], v[164:165]
	v_pk_mul_f32 v[96:97], v[96:97], v[166:167]
	v_pk_mul_f32 v[90:91], v[90:91], v[168:169]
	v_pk_mul_f32 v[92:93], v[92:93], v[170:171]
	v_cvt_pk_f16_f32 v176, v94, v95
	v_cvt_pk_f16_f32 v177, v96, v97
	v_cvt_pk_f16_f32 v178, v90, v91
	v_cvt_pk_f16_f32 v179, v92, v93
; __device__ __forceinline__ unsigned cvt_pk_bf16(float lo, float hi) { unsigned r; asm volatile("v_cvt_pk_f16_f32 %0, %1, %2" : "=v"(r) : "v"(lo), "v"(hi)); return r; }
;     __device__ __forceinline__ void operator()(const f32x4 (&acc)[2][2][4][2], const Unit& u, int wr, int wc, int fr, int fq) const {
;     ...
;                 const int row = row0 + ai * HALF + m * 16; const float sc = rs[row];
;                 const float sc2 = sc * sc, nsl = -1.4426950408889634f * sc;
;                 bf16_t* rowp = O + (size_t)row * ldc + col0;
;                 float h[8];
; #pragma unroll
;                 for (int n = 0; n < 2; ++n)
; #pragma unroll
;                     for (int e = 0; e < 4; ++e) { const float g = acc[ai][0][m][n][e], up = acc[ai][1][m][n][e];
;                         h[4 * n + e] = (g * up) * (sc2 * __builtin_amdgcn_rcpf(1.0f + __builtin_amdgcn_exp2f(g * nsl))); }
;                 u32x4 w; w.x = cvt_pk_bf16(h[0], h[1]); w.y = cvt_pk_bf16(h[2], h[3]); w.z = cvt_pk_bf16(h[4], h[5]); w.w = cvt_pk_bf16(h[6], h[7]);
;                 *(u32x4*)rowp = w;
	global_store_dwordx4 v174, v[176:179], s[6:7]
	v_add_u32_e32 v174, s98, v174
	v_mul_f32_e32 v188, 0xbfb8aa3b, v231
	v_mul_f32_e32 v190, v231, v231
	v_pk_mul_f32 v[164:165], v[70:71], v[188:189] op_sel_hi:[1,0]
	v_pk_mul_f32 v[166:167], v[72:73], v[188:189] op_sel_hi:[1,0]
	v_pk_mul_f32 v[168:169], v[66:67], v[188:189] op_sel_hi:[1,0]
	v_pk_mul_f32 v[170:171], v[68:69], v[188:189] op_sel_hi:[1,0]
	v_exp_f32_e32 v164, v164
	v_exp_f32_e32 v165, v165
	v_exp_f32_e32 v166, v166
	v_exp_f32_e32 v167, v167
	v_exp_f32_e32 v168, v168
	v_exp_f32_e32 v169, v169
	v_exp_f32_e32 v170, v170
	v_exp_f32_e32 v171, v171
	v_pk_add_f32 v[164:165], v[164:165], v[192:193]
	v_pk_add_f32 v[166:167], v[166:167], v[192:193]
	v_pk_add_f32 v[168:169], v[168:169], v[192:193]
	v_pk_add_f32 v[170:171], v[170:171], v[192:193]
	v_rcp_f32_e32 v164, v164
	v_rcp_f32_e32 v165, v165
	v_rcp_f32_e32 v166, v166
	v_rcp_f32_e32 v167, v167
	v_rcp_f32_e32 v168, v168
	v_rcp_f32_e32 v169, v169
	v_rcp_f32_e32 v170, v170
	v_rcp_f32_e32 v171, v171
	v_pk_mul_f32 v[164:165], v[164:165], v[190:191] op_sel_hi:[1,0]
	v_pk_mul_f32 v[166:167], v[166:167], v[190:191] op_sel_hi:[1,0]
	v_pk_mul_f32 v[168:169], v[168:169], v[190:191] op_sel_hi:[1,0]
	v_pk_mul_f32 v[170:171], v[170:171], v[190:191] op_sel_hi:[1,0]
	v_pk_mul_f32 v[78:79], v[70:71], v[78:79]
	v_pk_mul_f32 v[80:81], v[72:73], v[80:81]
	v_pk_mul_f32 v[74:75], v[66:67], v[74:75]
	v_pk_mul_f32 v[76:77], v[68:69], v[76:77]
	v_pk_mul_f32 v[78:79], v[78:79], v[164:165]
	v_pk_mul_f32 v[80:81], v[80:81], v[166:167]
	v_pk_mul_f32 v[74:75], v[74:75], v[168:169]
	v_pk_mul_f32 v[76:77], v[76:77], v[170:171]
	v_cvt_pk_f16_f32 v176, v78, v79
	v_cvt_pk_f16_f32 v177, v80, v81
	v_cvt_pk_f16_f32 v178, v74, v75
	v_cvt_pk_f16_f32 v179, v76, v77
	global_store_dwordx4 v174, v[176:179], s[6:7]
	v_mul_f32_e32 v188, 0xbfb8aa3b, v232
	v_mul_f32_e32 v190, v232, v232
	v_pk_mul_f32 v[164:165], v[54:55], v[188:189] op_sel_hi:[1,0]
	v_pk_mul_f32 v[166:167], v[56:57], v[188:189] op_sel_hi:[1,0]
	v_pk_mul_f32 v[168:169], v[50:51], v[188:189] op_sel_hi:[1,0]
	v_pk_mul_f32 v[170:171], v[52:53], v[188:189] op_sel_hi:[1,0]
	v_exp_f32_e32 v164, v164
	v_exp_f32_e32 v165, v165
	v_exp_f32_e32 v166, v166
	v_exp_f32_e32 v167, v167
	v_exp_f32_e32 v168, v168
	v_exp_f32_e32 v169, v169
	v_exp_f32_e32 v170, v170
	v_exp_f32_e32 v171, v171
	v_pk_add_f32 v[164:165], v[164:165], v[192:193]
	v_pk_add_f32 v[166:167], v[166:167], v[192:193]
	v_pk_add_f32 v[168:169], v[168:169], v[192:193]
	v_pk_add_f32 v[170:171], v[170:171], v[192:193]
	v_rcp_f32_e32 v164, v164
	v_rcp_f32_e32 v165, v165
	v_rcp_f32_e32 v166, v166
	v_rcp_f32_e32 v167, v167
	v_rcp_f32_e32 v168, v168
	v_rcp_f32_e32 v169, v169
	v_rcp_f32_e32 v170, v170
	v_rcp_f32_e32 v171, v171
	v_pk_mul_f32 v[164:165], v[164:165], v[190:191] op_sel_hi:[1,0]
	v_pk_mul_f32 v[166:167], v[166:167], v[190:191] op_sel_hi:[1,0]
	v_pk_mul_f32 v[168:169], v[168:169], v[190:191] op_sel_hi:[1,0]
	v_pk_mul_f32 v[170:171], v[170:171], v[190:191] op_sel_hi:[1,0]
	v_pk_mul_f32 v[62:63], v[54:55], v[62:63]
	v_pk_mul_f32 v[64:65], v[56:57], v[64:65]
	v_pk_mul_f32 v[58:59], v[50:51], v[58:59]
	v_pk_mul_f32 v[60:61], v[52:53], v[60:61]
	v_pk_mul_f32 v[62:63], v[62:63], v[164:165]
	v_pk_mul_f32 v[64:65], v[64:65], v[166:167]
	v_pk_mul_f32 v[58:59], v[58:59], v[168:169]
	v_pk_mul_f32 v[60:61], v[60:61], v[170:171]
	v_cvt_pk_f16_f32 v176, v62, v63
	v_cvt_pk_f16_f32 v177, v64, v65
	v_cvt_pk_f16_f32 v178, v58, v59
	v_cvt_pk_f16_f32 v179, v60, v61
	global_store_dwordx4 v175, v[176:179], s[6:7]
	v_add_u32_e32 v175, s98, v175
	v_mul_f32_e32 v188, 0xbfb8aa3b, v233
	v_mul_f32_e32 v190, v233, v233
	v_pk_mul_f32 v[164:165], v[38:39], v[188:189] op_sel_hi:[1,0]
	v_pk_mul_f32 v[166:167], v[40:41], v[188:189] op_sel_hi:[1,0]
	v_pk_mul_f32 v[168:169], v[34:35], v[188:189] op_sel_hi:[1,0]
	v_pk_mul_f32 v[170:171], v[36:37], v[188:189] op_sel_hi:[1,0]
	v_exp_f32_e32 v164, v164
	v_exp_f32_e32 v165, v165
	v_exp_f32_e32 v166, v166
	v_exp_f32_e32 v167, v167
	v_exp_f32_e32 v168, v168
	v_exp_f32_e32 v169, v169
	v_exp_f32_e32 v170, v170
	v_exp_f32_e32 v171, v171
	v_pk_add_f32 v[164:165], v[164:165], v[192:193]
	v_pk_add_f32 v[166:167], v[166:167], v[192:193]
	v_pk_add_f32 v[168:169], v[168:169], v[192:193]
	v_pk_add_f32 v[170:171], v[170:171], v[192:193]
	v_rcp_f32_e32 v164, v164
	v_rcp_f32_e32 v165, v165
	v_rcp_f32_e32 v166, v166
	v_rcp_f32_e32 v167, v167
	v_rcp_f32_e32 v168, v168
	v_rcp_f32_e32 v169, v169
; __device__ __forceinline__ unsigned cvt_pk_bf16(float lo, float hi) { unsigned r; asm volatile("v_cvt_pk_f16_f32 %0, %1, %2" : "=v"(r) : "v"(lo), "v"(hi)); return r; }
; #define PG8_BAR __builtin_amdgcn_s_barrier()
; template <class Epi, class Sched, bool ALIGN_EPI = false, bool SP2 = false>
; __device__ __forceinline__ void gemm_phase(PG8_LAS unsigned char* lds, const Gemm g, const Sched& S, const Epi& E) {
;     ...
;         if constexpr (!Epi::AFTER_DRAIN) { E(acc, cur, wr, wc, fr, fq); S.done(cur); }
;         if (!has_next) break;
; #pragma unroll
;         for (int a = 0; a < 2; ++a)
; #pragma unroll
;             for (int b = 0; b < 2; ++b)
; #pragma unroll
;                 for (int m = 0; m < 4; ++m)
; #pragma unroll
;                     for (int n = 0; n < 2; ++n) acc[a][b][m][n] = (f32x4){0.f, 0.f, 0.f, 0.f};
;         cur = nxt; cA = nA; cB = nB; ++ui;
;         if constexpr (ALIGN_EPI) { if (wr == 1) PG8_BAR; }
;     __device__ __forceinline__ void operator()(const f32x4 (&acc)[2][2][4][2], const Unit& u, int wr, int wc, int fr, int fq) const {
;     ...
;                 const int row = row0 + ai * HALF + m * 16; const float sc = rs[row];
;                 const float sc2 = sc * sc, nsl = -1.4426950408889634f * sc;
;                 bf16_t* rowp = O + (size_t)row * ldc + col0;
;                 float h[8];
; #pragma unroll
;                 for (int n = 0; n < 2; ++n)
; #pragma unroll
;                     for (int e = 0; e < 4; ++e) { const float g = acc[ai][0][m][n][e], up = acc[ai][1][m][n][e];
;                         h[4 * n + e] = (g * up) * (sc2 * __builtin_amdgcn_rcpf(1.0f + __builtin_amdgcn_exp2f(g * nsl))); }
;                 u32x4 w; w.x = cvt_pk_bf16(h[0], h[1]); w.y = cvt_pk_bf16(h[2], h[3]); w.z = cvt_pk_bf16(h[4], h[5]); w.w = cvt_pk_bf16(h[6], h[7]);
;                 *(u32x4*)rowp = w;
	v_rcp_f32_e32 v170, v170
	v_rcp_f32_e32 v171, v171
	v_pk_mul_f32 v[164:165], v[164:165], v[190:191] op_sel_hi:[1,0]
	v_pk_mul_f32 v[166:167], v[166:167], v[190:191] op_sel_hi:[1,0]
	v_pk_mul_f32 v[168:169], v[168:169], v[190:191] op_sel_hi:[1,0]
	v_pk_mul_f32 v[170:171], v[170:171], v[190:191] op_sel_hi:[1,0]
	v_pk_mul_f32 v[46:47], v[38:39], v[46:47]
	v_pk_mul_f32 v[48:49], v[40:41], v[48:49]
	v_pk_mul_f32 v[42:43], v[34:35], v[42:43]
	v_pk_mul_f32 v[44:45], v[36:37], v[44:45]
	v_pk_mul_f32 v[46:47], v[46:47], v[164:165]
	v_pk_mul_f32 v[48:49], v[48:49], v[166:167]
	v_pk_mul_f32 v[42:43], v[42:43], v[168:169]
	v_pk_mul_f32 v[44:45], v[44:45], v[170:171]
	v_cvt_pk_f16_f32 v176, v46, v47
	v_cvt_pk_f16_f32 v177, v48, v49
	v_cvt_pk_f16_f32 v178, v42, v43
	v_cvt_pk_f16_f32 v179, v44, v45
	global_store_dwordx4 v175, v[176:179], s[6:7]
	v_add_u32_e32 v175, s98, v175
	v_mul_f32_e32 v188, 0xbfb8aa3b, v234
	v_mul_f32_e32 v190, v234, v234
	v_pk_mul_f32 v[164:165], v[22:23], v[188:189] op_sel_hi:[1,0]
	v_pk_mul_f32 v[166:167], v[24:25], v[188:189] op_sel_hi:[1,0]
	v_pk_mul_f32 v[168:169], v[18:19], v[188:189] op_sel_hi:[1,0]
	v_pk_mul_f32 v[170:171], v[20:21], v[188:189] op_sel_hi:[1,0]
	v_exp_f32_e32 v164, v164
	v_exp_f32_e32 v165, v165
	v_exp_f32_e32 v166, v166
	v_exp_f32_e32 v167, v167
	v_exp_f32_e32 v168, v168
	v_exp_f32_e32 v169, v169
	v_exp_f32_e32 v170, v170
	v_exp_f32_e32 v171, v171
	v_pk_add_f32 v[164:165], v[164:165], v[192:193]
	v_pk_add_f32 v[166:167], v[166:167], v[192:193]
	v_pk_add_f32 v[168:169], v[168:169], v[192:193]
	v_pk_add_f32 v[170:171], v[170:171], v[192:193]
	v_rcp_f32_e32 v164, v164
	v_rcp_f32_e32 v165, v165
	v_rcp_f32_e32 v166, v166
	v_rcp_f32_e32 v167, v167
	v_rcp_f32_e32 v168, v168
	v_rcp_f32_e32 v169, v169
	v_rcp_f32_e32 v170, v170
	v_rcp_f32_e32 v171, v171
	v_pk_mul_f32 v[164:165], v[164:165], v[190:191] op_sel_hi:[1,0]
	v_pk_mul_f32 v[166:167], v[166:167], v[190:191] op_sel_hi:[1,0]
	v_pk_mul_f32 v[168:169], v[168:169], v[190:191] op_sel_hi:[1,0]
	v_pk_mul_f32 v[170:171], v[170:171], v[190:191] op_sel_hi:[1,0]
	v_pk_mul_f32 v[30:31], v[22:23], v[30:31]
	v_pk_mul_f32 v[32:33], v[24:25], v[32:33]
	v_pk_mul_f32 v[26:27], v[18:19], v[26:27]
	v_pk_mul_f32 v[28:29], v[20:21], v[28:29]
	v_pk_mul_f32 v[30:31], v[30:31], v[164:165]
	v_pk_mul_f32 v[32:33], v[32:33], v[166:167]
	v_pk_mul_f32 v[26:27], v[26:27], v[168:169]
	v_pk_mul_f32 v[28:29], v[28:29], v[170:171]
	v_cvt_pk_f16_f32 v176, v30, v31
	v_cvt_pk_f16_f32 v177, v32, v33
	v_cvt_pk_f16_f32 v178, v26, v27
	v_cvt_pk_f16_f32 v179, v28, v29
	global_store_dwordx4 v175, v[176:179], s[6:7]
	v_add_u32_e32 v175, s98, v175
	v_mul_f32_e32 v188, 0xbfb8aa3b, v235
	v_mul_f32_e32 v190, v235, v235
	v_pk_mul_f32 v[164:165], v[6:7], v[188:189] op_sel_hi:[1,0]
	v_pk_mul_f32 v[166:167], v[8:9], v[188:189] op_sel_hi:[1,0]
	v_pk_mul_f32 v[168:169], v[2:3], v[188:189] op_sel_hi:[1,0]
	v_pk_mul_f32 v[170:171], v[4:5], v[188:189] op_sel_hi:[1,0]
	v_exp_f32_e32 v164, v164
	v_exp_f32_e32 v165, v165
	v_exp_f32_e32 v166, v166
	v_exp_f32_e32 v167, v167
	v_exp_f32_e32 v168, v168
	v_exp_f32_e32 v169, v169
	v_exp_f32_e32 v170, v170
	v_exp_f32_e32 v171, v171
	v_pk_add_f32 v[164:165], v[164:165], v[192:193]
	v_pk_add_f32 v[166:167], v[166:167], v[192:193]
	v_pk_add_f32 v[168:169], v[168:169], v[192:193]
	v_pk_add_f32 v[170:171], v[170:171], v[192:193]
	v_rcp_f32_e32 v164, v164
	v_rcp_f32_e32 v165, v165
	v_rcp_f32_e32 v166, v166
	v_rcp_f32_e32 v167, v167
	v_rcp_f32_e32 v168, v168
	v_rcp_f32_e32 v169, v169
	v_rcp_f32_e32 v170, v170
	v_rcp_f32_e32 v171, v171
	v_pk_mul_f32 v[164:165], v[164:165], v[190:191] op_sel_hi:[1,0]
	v_pk_mul_f32 v[166:167], v[166:167], v[190:191] op_sel_hi:[1,0]
	v_pk_mul_f32 v[168:169], v[168:169], v[190:191] op_sel_hi:[1,0]
	v_pk_mul_f32 v[170:171], v[170:171], v[190:191] op_sel_hi:[1,0]
	v_pk_mul_f32 v[14:15], v[6:7], v[14:15]
	v_pk_mul_f32 v[16:17], v[8:9], v[16:17]
	v_pk_mul_f32 v[10:11], v[2:3], v[10:11]
	v_pk_mul_f32 v[12:13], v[4:5], v[12:13]
	v_pk_mul_f32 v[14:15], v[14:15], v[164:165]
	v_pk_mul_f32 v[16:17], v[16:17], v[166:167]
	v_pk_mul_f32 v[10:11], v[10:11], v[168:169]
	v_pk_mul_f32 v[12:13], v[12:13], v[170:171]
	v_cvt_pk_f16_f32 v176, v14, v15
	v_cvt_pk_f16_f32 v177, v16, v17
	v_cvt_pk_f16_f32 v178, v10, v11
	v_cvt_pk_f16_f32 v179, v12, v13
	global_store_dwordx4 v175, v[176:179], s[6:7]
	s_cbranch_vccnz .LBB0_1010
	s_andn2_b64 vcc, exec, s[4:5]
	s_cbranch_vccnz .LBB0_1009
	s_barrier
	s_branch .LBB0_1009
